# LRU sample-unit prologue: block-weight LDS writes wait at the end of the prologue (all prologue loads in flight together), as already done for prompt units
# speedup vs baseline: 1.0053x; 1.0053x over previous
.LBB0_278:
	s_and_b64 vcc, exec, s[4:5]
	s_cbranch_vccz .LBB0_245
	s_mov_b64 s[12:13], s[26:27]
	s_mov_b64 s[50:51], s[26:27]
	s_mov_b32 s4, 25
	s_ashr_i32 s5, s4, 31
	s_and_b32 s19, s48, 15
	s_lshl_b64 s[4:5], s[4:5], 3
	s_add_u32 s4, s0, s4
	s_addc_u32 s5, s1, s5
	s_load_dwordx2 s[14:15], s[4:5], 0x0
	s_mov_b32 s4, 26
	s_ashr_i32 s5, s4, 31
	s_lshl_b64 s[4:5], s[4:5], 3
	s_add_u32 s4, s0, s4
	s_addc_u32 s5, s1, s5
	s_load_dwordx2 s[16:17], s[4:5], 0x0
	s_mov_b32 s4, 28
	s_ashr_i32 s5, s4, 31
	s_lshl_b64 s[4:5], s[4:5], 3
	s_add_u32 s4, s0, s4
	s_addc_u32 s5, s1, s5
	s_load_dwordx2 s[10:11], s[4:5], 0x0
	s_mov_b32 s4, 30
	s_ashr_i32 s5, s4, 31
	s_lshl_b64 s[4:5], s[4:5], 3
	s_add_u32 s4, s0, s4
	s_addc_u32 s5, s1, s5
	s_load_dwordx2 s[34:35], s[4:5], 0x0
	s_mov_b32 s4, 31
	s_ashr_i32 s5, s4, 31
	s_lshl_b64 s[4:5], s[4:5], 3
	s_add_u32 s4, s0, s4
	s_addc_u32 s5, s1, s5
	s_load_dwordx2 s[38:39], s[4:5], 0x0
	s_mov_b32 s28, 7
	s_mov_b32 s22, 8
	s_mov_b64 s[4:5], s[30:31]
	s_mov_b64 s[4:5], s[30:31]
	s_mov_b64 s[20:21], s[26:27]
	s_mov_b64 s[4:5], s[26:27]
	v_mov_b32_e32 v92, v179
	v_mov_b32_e32 v37, v0
	v_readfirstlane_b32 s18, v92
	s_ashr_i32 s23, s18, 8
	s_lshl_b32 s29, s23, 16
	s_add_i32 s40, s29, 0
	s_lshl_b32 s29, s23, 1
	s_add_i32 s52, s29, s42
	s_lshl_b32 s29, s19, 13
	v_lshlrev_b32_e32 v1, 3, v92
	s_add_u32 s50, s50, s29
	v_and_b32_e32 v40, 56, v1
	s_addc_u32 s51, s51, 0
	v_lshlrev_b32_e32 v36, 1, v40
	v_lshl_add_u64 v[2:3], s[50:51], 0, v[36:37]
	s_ashr_i32 s53, s52, 31
	s_waitcnt vmcnt(4)
	v_lshl_add_u64 v[6:7], v[2:3], 0, s[56:57]
	v_bfe_u32 v93, v92, 3, 5
	s_lshl_b64 s[50:51], s[52:53], 17
	v_lshl_add_u64 v[8:9], v[6:7], 0, s[50:51]
	v_lshlrev_b32_e32 v10, 7, v93
	v_mov_b32_e32 v11, v0
	s_waitcnt lgkmcnt(0)
	s_barrier
	v_lshl_add_u64 v[2:3], v[8:9], 0, v[10:11]
	global_load_dwordx4 v[160:163], v[2:3], off
	v_mul_u32_u24_e32 v1, 0x48, v93
	v_add_lshl_u32 v1, v1, v40, 1
	v_or_b32_e32 v95, 32, v93
	v_add_u32_e32 v94, s40, v1
	s_waitcnt vmcnt(4)
	v_lshlrev_b32_e32 v12, 7, v95
	v_mov_b32_e32 v13, v0
	s_or_b32 s50, s52, 1
	s_ashr_i32 s51, s50, 31
	v_add_u32_e32 v1, 0x1200, v1
	s_lshl_b64 s[50:51], s[50:51], 17
	v_add_u32_e32 v96, s40, v1
	v_lshl_add_u64 v[6:7], v[6:7], 0, s[50:51]
	s_lshl_b32 s62, s19, 6
	s_lshl_b32 s19, s23, 10
	s_add_i32 s19, s19, s43
	v_and_b32_e32 v41, 15, v92
	s_or_b32 s19, s19, s62
	v_mov_b32_e32 v1, 63
	v_lshl_add_u64 v[148:149], v[8:9], 0, v[12:13]
	global_load_dwordx4 v[148:151], v[148:149], off
	v_lshl_add_u64 v[152:153], v[6:7], 0, v[10:11]
	global_load_dwordx4 v[152:155], v[152:153], off
	v_lshl_add_u64 v[156:157], v[6:7], 0, v[12:13]
	global_load_dwordx4 v[156:159], v[156:157], off
	v_or_b32_e32 v2, s19, v41
	v_ashrrev_i32_e32 v3, 31, v2
	v_lshlrev_b64 v[2:3], 2, v[2:3]
	s_waitcnt lgkmcnt(0)
	v_lshl_add_u64 v[4:5], s[10:11], 0, v[2:3]
	v_lshl_add_u64 v[6:7], s[34:35], 0, v[2:3]
	v_lshl_add_u64 v[2:3], s[38:39], 0, v[2:3]
	global_load_dword v97, v[4:5], off
	global_load_dword v98, v[6:7], off
	global_load_dword v45, v[2:3], off
	global_load_dword v99, v[4:5], off offset:64
	global_load_dword v100, v[6:7], off offset:64
	global_load_dword v44, v[2:3], off offset:64
	global_load_dword v101, v[4:5], off offset:128
	global_load_dword v102, v[6:7], off offset:128
	global_load_dword v42, v[2:3], off offset:128
	global_load_dword v103, v[4:5], off offset:192
	global_load_dword v104, v[6:7], off offset:192
	global_load_dword v43, v[2:3], off offset:192
	v_cmp_lt_u32_sdwa s[10:11], v92, v233 src0_sel:BYTE_0 src1_sel:DWORD
	v_cmp_gt_u32_sdwa s[34:35], v92, v1 src0_sel:BYTE_0 src1_sel:DWORD
	v_mov_b64_e32 v[4:5], s[62:63]
	s_and_saveexec_b64 s[38:39], s[34:35]
	s_xor_b64 s[34:35], exec, s[38:39]
	v_mov_b64_e32 v[4:5], s[62:63]
	s_or_saveexec_b64 s[34:35], s[34:35]
	s_ashr_i32 s19, s48, 4
	v_mov_b32_e32 v91, 0
	s_xor_b64 exec, exec, s[34:35]
	s_cbranch_execz .LBB0_283
	s_ashr_i32 s29, s28, 31
	s_lshl_b64 s[28:29], s[28:29], 3
	s_add_u32 s28, s0, s28
	s_addc_u32 s29, s1, s29
	s_ashr_i32 s23, s22, 31
	s_lshl_b64 s[22:23], s[22:23], 3
	s_add_u32 s22, s0, s22
	s_addc_u32 s23, s1, s23
	s_load_dwordx2 s[28:29], s[28:29], 0x0
	s_nop 0
	s_load_dwordx2 s[22:23], s[22:23], 0x0
	s_cmpk_lt_u32 s18, 0x100
	v_readlane_b32 s38, v254, 60
	v_lshlrev_b32_sdwa v1, v236, v92 dst_sel:DWORD dst_unused:UNUSED_PAD src0_sel:DWORD src1_sel:BYTE_0
	v_readlane_b32 s39, v254, 61
	s_waitcnt lgkmcnt(0)
	s_cselect_b32 s29, s29, s23
	s_cselect_b32 s28, s28, s22
	s_lshl_b32 s22, s19, 1
	s_add_i32 s22, s22, s38
	s_ashr_i32 s23, s22, 31
	s_lshl_b64 s[22:23], s[22:23], 12
	s_add_u32 s22, s28, s22
	s_addc_u32 s23, s29, s23
	s_lshl_b32 s28, s62, 2
	s_add_u32 s22, s22, s28
	s_addc_u32 s23, s23, 0
	global_load_dword v91, v1, s[22:23]

.LBB0_289:
	s_or_b64 exec, exec, s[28:29]
	s_waitcnt vmcnt(14)
	v_mul_f32_e64 v1, |v45|, s87
	v_exp_f32_e32 v1, v1
	s_add_u32 s19, s20, 0x7100000
	s_addc_u32 s21, s21, 0
	s_add_u32 s28, s4, 0x9100000
	v_add_f32_e32 v1, 1.0, v1
	v_cmp_gt_f32_e32 vcc, s84, v1
	s_addc_u32 s29, s5, 0
	v_bfe_u32 v46, v92, 4, 2
	v_cndmask_b32_e64 v2, 0, 32, vcc
	v_ldexp_f32 v1, v1, v2
	v_log_f32_e32 v1, v1
	v_max_f32_e64 v2, -v45, -v45
	v_cndmask_b32_e32 v45, 0, v232, vcc
	v_max_f32_e32 v2, 0, v2
	v_mul_f32_e32 v3, 0x3f317217, v1
	v_fma_f32 v3, v1, s80, -v3
	v_fmac_f32_e32 v3, 0x3377d1cf, v1
	v_fmac_f32_e32 v3, 0x3f317217, v1
	v_cmp_lt_f32_e64 s[4:5], |v1|, s81
	v_or_b32_e32 v56, 32, v41
	s_mov_b32 s20, 0
	v_cndmask_b32_e64 v1, v1, v3, s[4:5]
	s_waitcnt vmcnt(11)
	v_mul_f32_e64 v3, |v44|, s87
	v_exp_f32_e32 v3, v3
	v_sub_f32_e32 v1, v1, v45
	v_add_f32_e32 v1, v2, v1
	v_mul_f32_e32 v105, 0xc1000000, v1
	v_add_f32_e32 v2, 1.0, v3
	v_cmp_gt_f32_e32 vcc, s84, v2
	v_max_f32_e64 v1, -v44, -v44
	v_max_f32_e32 v1, 0, v1
	v_cndmask_b32_e64 v3, 0, 32, vcc
	v_ldexp_f32 v2, v2, v3
	v_log_f32_e32 v2, v2
	v_cndmask_b32_e32 v44, 0, v232, vcc
	v_mov_b32_e32 v45, v0
	v_or_b32_e32 v115, s34, v93
	v_mul_f32_e32 v3, 0x3f317217, v2
	v_fma_f32 v3, v2, s80, -v3
	v_fmac_f32_e32 v3, 0x3377d1cf, v2
	v_fmac_f32_e32 v3, 0x3f317217, v2
	v_cmp_lt_f32_e64 s[4:5], |v2|, s81
	v_or_b32_e32 v116, s34, v95
	s_nop 0
	v_cndmask_b32_e64 v2, v2, v3, s[4:5]
	s_waitcnt vmcnt(8)
	v_mul_f32_e64 v3, |v42|, s87
	v_exp_f32_e32 v3, v3
	v_sub_f32_e32 v2, v2, v44
	v_add_f32_e32 v1, v1, v2
	v_mul_f32_e32 v106, 0xc1000000, v1
	v_add_f32_e32 v2, 1.0, v3
	v_cmp_gt_f32_e32 vcc, s84, v2
	v_max_f32_e64 v1, -v42, -v42
	v_max_f32_e32 v1, 0, v1
	v_cndmask_b32_e64 v3, 0, 32, vcc
	v_ldexp_f32 v2, v2, v3
	v_log_f32_e32 v2, v2
	v_cndmask_b32_e32 v42, 0, v232, vcc
	v_and_b32_e32 v44, 7, v92
	v_lshl_add_u32 v48, v44, 5, s40
	v_mul_f32_e32 v3, 0x3f317217, v2
	v_fma_f32 v3, v2, s80, -v3
	v_fmac_f32_e32 v3, 0x3377d1cf, v2
	v_fmac_f32_e32 v3, 0x3f317217, v2
	v_cmp_lt_f32_e64 s[4:5], |v2|, s81
	v_lshlrev_b32_e32 v44, 4, v44
	s_nop 0
	v_cndmask_b32_e64 v2, v2, v3, s[4:5]
	s_waitcnt vmcnt(5)
	v_mul_f32_e64 v3, |v43|, s87
	v_exp_f32_e32 v3, v3
	v_sub_f32_e32 v2, v2, v42
	v_add_f32_e32 v1, v1, v2
	v_mul_f32_e32 v107, 0xc1000000, v1
	v_add_f32_e32 v2, 1.0, v3
	v_cmp_gt_f32_e32 vcc, s84, v2
	v_max_f32_e64 v1, -v43, -v43
	v_max_f32_e32 v1, 0, v1
	v_cndmask_b32_e64 v3, 0, 32, vcc
	v_ldexp_f32 v2, v2, v3
	v_log_f32_e32 v2, v2
	s_nop 0
	v_mul_f32_e32 v3, 0x3f317217, v2
	v_fma_f32 v3, v2, s80, -v3
	v_fmac_f32_e32 v3, 0x3377d1cf, v2
	v_fmac_f32_e32 v3, 0x3f317217, v2
	v_cmp_lt_f32_e64 s[4:5], |v2|, s81
	s_nop 1
	v_cndmask_b32_e64 v2, v2, v3, s[4:5]
	v_cndmask_b32_e32 v3, 0, v232, vcc
	v_sub_f32_e32 v2, v2, v3
	s_and_b64 s[4:5], s[12:13], exec
	v_add_f32_e32 v1, v1, v2
	s_cselect_b32 s5, s21, s29
	s_cselect_b32 s4, s19, s28
	s_lshl_b64 s[28:29], s[6:7], 2
	v_mul_f32_e32 v108, 0xc1000000, v1
	v_or_b32_e32 v1, s62, v40
	s_add_u32 s16, s16, s28
	s_addc_u32 s17, s17, s29
	v_lshlrev_b32_e32 v2, 2, v1
	v_mov_b32_e32 v3, v0
	v_lshl_add_u64 v[76:77], s[16:17], 0, v[2:3]
	v_lshl_add_u64 v[2:3], s[14:15], 0, v[2:3]
	s_lshr_b32 s14, s18, 2
	s_and_b32 s14, s14, 48
	v_lshlrev_b32_e32 v40, 4, v46
	v_lshl_or_b32 v46, v46, 2, s14
	v_lshl_add_u64 v[80:81], v[2:3], 0, s[8:9]
	v_mul_u32_u24_e32 v2, 0x48, v46
	v_lshl_add_u64 v[42:43], s[4:5], 0, v[38:39]
	v_or_b32_e32 v3, v2, v41
	v_lshl_add_u64 v[78:79], v[42:43], 0, v[44:45]
	v_lshlrev_b32_e32 v43, 1, v3
	v_mad_u32_u24 v3, v46, s64, v41
	v_mad_u32_u24 v44, v46, s86, s86
	v_lshl_add_u32 v109, v3, 2, s40
	v_or_b32_e32 v3, 1, v46
	v_add_u32_e32 v45, v44, v41
	v_mad_i32_i24 v3, v3, -7, v45
	v_lshl_add_u32 v110, v3, 2, s40
	v_mad_u32_u24 v3, v46, s86, v234
	v_or_b32_e32 v50, 3, v46
	v_mad_u32_u24 v46, v46, s86, v235
	v_add_u32_e32 v51, v46, v41
	v_mad_i32_i24 v50, v50, -7, v51
	s_mov_b64 s[4:5], 0x1000
	v_lshl_add_u32 v112, v50, 2, s40
	v_or_b32_e32 v50, 16, v41
	v_or_b32_e32 v1, s14, v41
	v_lshl_add_u64 v[82:83], v[80:81], 0, s[4:5]
	s_mov_b64 s[4:5], 0x2000
	v_mad_u32_u24 v42, v41, s85, v40
	v_lshlrev_b32_e32 v49, 1, v45
	v_or_b32_e32 v45, v3, v41
	v_or_b32_e32 v53, v2, v50
	v_or_b32_e32 v41, 48, v41
	v_mul_u32_u24_e32 v1, 0x90, v1
	v_add_u32_e32 v47, s40, v40
	v_lshl_add_u64 v[84:85], v[80:81], 0, s[4:5]
	s_mov_b64 s[4:5], 0x3000
	v_lshlrev_b32_e32 v45, 1, v45
	v_lshlrev_b32_e32 v52, 1, v51
	v_mad_u32_u24 v51, v50, s85, v40
	v_lshlrev_b32_e32 v53, 1, v53
	v_add_lshl_u32 v54, v44, v50, 1
	v_add_lshl_u32 v55, v3, v50, 1
	v_add_lshl_u32 v50, v46, v50, 1
	v_mad_u32_u24 v57, v56, s85, v40
	v_add_lshl_u32 v58, v2, v56, 1
	v_add_lshl_u32 v59, v44, v56, 1
	v_add_lshl_u32 v60, v3, v56, 1
	v_add_lshl_u32 v56, v46, v56, 1
	v_mad_u32_u24 v40, v41, s85, v40
	v_add_lshl_u32 v61, v2, v41, 1
	v_add_lshl_u32 v44, v44, v41, 1
	v_add_lshl_u32 v62, v3, v41, 1
	v_add_lshl_u32 v41, v46, v41, 1
	v_mul_u32_u24_e32 v46, 0x104, v93
	v_lshl_add_u64 v[2:3], s[22:23], 0, v[38:39]
	v_lshl_add_u64 v[86:87], v[80:81], 0, s[4:5]
	v_add_u32_e32 v111, 0x208, v109
	v_add_u32_e32 v113, 0x104, v109
	v_add_u32_e32 v114, 0x30c, v109
	v_lshl_add_u64 v[88:89], v[2:3], 0, v[36:37]
	v_add_u32_e32 v117, v47, v1
	v_add_u32_e32 v118, s40, v42
	v_add_u32_e32 v119, s40, v43
	v_add_u32_e32 v120, s40, v49
	v_add_u32_e32 v121, s40, v45
	v_add_u32_e32 v122, s40, v52
	v_add_u32_e32 v123, s40, v51
	v_add_u32_e32 v124, s40, v53
	v_add_u32_e32 v125, s40, v54
	v_add_u32_e32 v126, s40, v55
	v_add_u32_e32 v127, s40, v50
	v_add_u32_e32 v128, s40, v57
	v_add_u32_e32 v129, s40, v58
	v_add_u32_e32 v130, s40, v59
	v_add_u32_e32 v131, s40, v60
	v_add_u32_e32 v132, s40, v56
	v_add_u32_e32 v133, s40, v40
	v_add_u32_e32 v134, s40, v61
	v_add_u32_e32 v135, s40, v44
	v_add_u32_e32 v136, s40, v62
	v_add_u32_e32 v137, s40, v41
	v_add_u32_e32 v138, v48, v46
	s_waitcnt vmcnt(0)
	ds_write_b128 v94, v[160:163] offset:9216
	ds_write_b128 v96, v[148:151] offset:9216
	ds_write_b128 v94, v[152:155] offset:18432
	ds_write_b128 v96, v[156:159] offset:18432
	s_branch .LBB0_291
